# hoisted serialized loads in S5 carry-prefix loops, s5_end_gemm, gate_gemm K loops and final rmsnorm gain loads
# speedup vs baseline: 1.0095x; 1.0095x over previous
; __device__ __forceinline__ float ep_rstd(const rowss_t* rowss, int row) { return __builtin_amdgcn_rsqf((float)rowss[row] * (1.0f / 16777216.0f) * (1.0f / 2048.0f) + 1e-6f); }
; DI f32x4 mfma16(bf16x8 a, bf16x8 b, f32x4 c) { return __builtin_amdgcn_mfma_f32_16x16x32_bf16(a, b, c, 0, 0, 0); }
; template <int NT> DI void gate_gemm(const Ctx& C, const bf16* HN, const bf16* WgT, const float* bias, float* G, const pg8::rowss_t* rowss) {
;     ...
;         const bf16* a = HN + (size_t)(rt * 16 + (lane & 15)) * D + (lane >> 4) * 8;
;         const bf16* b = WgT + (size_t)(lane & 15) * D + (lane >> 4) * 8;
; #pragma unroll 4
;         for (int k = 0; k < D / 32; ++k) { const bf16x8 av = *(const bf16x8*)(a + 32 * k);
; #pragma unroll
;             for (int n = 0; n < NT; ++n) acc[n] = mfma16(av, *(const bf16x8*)(b + (size_t)n * 16 * D + 32 * k), acc[n]); }
; #pragma unroll
;         for (int n = 0; n < NT; ++n)
; #pragma unroll
;             for (int j = 0; j < 4; ++j) { const int row = rt * 16 + (lane >> 4) * 4 + j, col = n * 16 + (lane & 15); G[(size_t)row * (16 * NT) + col] = acc[n][j] * pg8::ep_rstd(rowss, row) + (bias ? bias[col] : 0.f); }
.LBB0_381:
	v_lshl_add_u64 v[24:25], v[20:21], 0, s[8:9]
	v_add_co_u32_e32 v32, vcc, 0xb000000, v24
	v_lshl_add_u64 v[34:35], v[14:15], 0, s[8:9]
	s_nop 0
	v_addc_co_u32_e32 v33, vcc, 0, v25, vcc
	v_add_co_u32_e32 v36, vcc, 0x600000, v34
	s_add_u32 s8, s8, 0x100
	s_nop 0
	v_addc_co_u32_e32 v37, vcc, 0, v35, vcc
	v_add_co_u32_e32 v34, vcc, 0x610000, v34
	s_addc_u32 s9, s9, 0
	s_nop 0
	v_addc_co_u32_e32 v35, vcc, 0, v35, vcc
	s_cmpk_eq_i32 s8, 0x1000
	global_load_dwordx4 v[80:83], v[32:33], off
	global_load_dwordx4 v[96:99], v[36:37], off
	global_load_dwordx4 v[100:103], v[34:35], off
	global_load_dwordx4 v[84:87], v[32:33], off offset:64
	global_load_dwordx4 v[104:107], v[36:37], off offset:64
	global_load_dwordx4 v[108:111], v[34:35], off offset:64
	global_load_dwordx4 v[88:91], v[32:33], off offset:128
	global_load_dwordx4 v[112:115], v[36:37], off offset:128
	global_load_dwordx4 v[116:119], v[34:35], off offset:128
	global_load_dwordx4 v[92:95], v[32:33], off offset:192
	global_load_dwordx4 v[120:123], v[36:37], off offset:192
	global_load_dwordx4 v[124:127], v[34:35], off offset:192
	s_waitcnt vmcnt(10) lgkmcnt(0)
	v_mfma_f32_16x16x32_bf16 v[10:13], v[80:83], v[96:99], v[10:13]
	s_waitcnt vmcnt(9)
	v_mfma_f32_16x16x32_bf16 v[6:9], v[80:83], v[100:103], v[6:9]
	s_waitcnt vmcnt(7)
	v_mfma_f32_16x16x32_bf16 v[10:13], v[84:87], v[104:107], v[10:13]
	s_waitcnt vmcnt(6)
	v_mfma_f32_16x16x32_bf16 v[6:9], v[84:87], v[108:111], v[6:9]
	s_waitcnt vmcnt(4)
	v_mfma_f32_16x16x32_bf16 v[10:13], v[88:91], v[112:115], v[10:13]
	s_waitcnt vmcnt(3)
	v_mfma_f32_16x16x32_bf16 v[6:9], v[88:91], v[116:119], v[6:9]
	s_waitcnt vmcnt(1)
	v_mfma_f32_16x16x32_bf16 v[10:13], v[92:95], v[120:123], v[10:13]
	s_waitcnt vmcnt(0)
	v_mfma_f32_16x16x32_bf16 v[6:9], v[92:95], v[124:127], v[6:9]
	s_cbranch_scc0 .LBB0_381
	v_lshl_or_b32 v20, s10, 4, v22
	v_ashrrev_i32_e32 v21, 31, v20
	v_lshl_add_u64 v[24:25], v[20:21], 3, s[0:1]
	global_load_dwordx4 v[24:27], v[24:25], off
	v_or_b32_e32 v30, 2, v20
	v_ashrrev_i32_e32 v31, 31, v30
	v_readlane_b32 s6, v253, 21
	s_add_i32 s10, s10, s6
	v_readlane_b32 s6, v254, 30
	s_cmpk_gt_i32 s10, 0x3ff
	v_readlane_b32 s7, v253, 22
	v_add_u32_e32 v18, s6, v18
	s_waitcnt vmcnt(0) lgkmcnt(0)
	v_ffbh_u32_e32 v2, v25
	v_min_u32_e32 v2, 32, v2
	v_lshlrev_b64 v[24:25], v2, v[24:25]
	v_min_u32_e32 v5, 1, v24
	v_or_b32_e32 v5, v25, v5
	v_cvt_f32_u32_e32 v5, v5
	v_sub_u32_e32 v2, 32, v2
	v_lshlrev_b64 v[24:25], 7, v[20:21]
	v_lshl_add_u64 v[28:29], v[0:1], 0, v[24:25]
	v_ldexp_f32 v2, v5, v2
	v_mul_f32_e32 v2, 0x33800000, v2
	v_fmamk_f32 v2, v2, 0x3a000000, v209
	v_rsq_f32_e32 v2, v2
	v_or_b32_e32 v24, 1, v20
	v_ashrrev_i32_e32 v25, 31, v24
	v_or_b32_e32 v20, 3, v20
	v_fma_f32 v5, v10, v2, 0
	global_store_dword v[28:29], v5, off
	v_ffbh_u32_e32 v5, v27
	v_min_u32_e32 v5, 32, v5
	v_lshlrev_b64 v[26:27], v5, v[26:27]
	v_min_u32_e32 v10, 1, v26
	v_or_b32_e32 v10, v27, v10
	v_cvt_f32_u32_e32 v10, v10
	v_sub_u32_e32 v5, 32, v5
	v_fma_f32 v2, v6, v2, 0
	global_store_dword v[28:29], v2, off offset:64
	v_ldexp_f32 v5, v10, v5
	v_mul_f32_e32 v5, 0x33800000, v5
	v_fmamk_f32 v5, v5, 0x3a000000, v209
	v_rsq_f32_e32 v5, v5
	s_nop 0
	v_fma_f32 v19, v11, v5, 0
	v_lshlrev_b64 v[10:11], 7, v[24:25]
	v_lshl_add_u64 v[24:25], v[30:31], 3, s[0:1]
	global_load_dwordx4 v[24:27], v[24:25], off
	v_lshl_add_u64 v[10:11], v[0:1], 0, v[10:11]
	global_store_dword v[10:11], v19, off
	v_fma_f32 v2, v7, v5, 0
	global_store_dword v[10:11], v2, off offset:64
	s_waitcnt vmcnt(0) lgkmcnt(0)
	v_ffbh_u32_e32 v19, v25
	v_min_u32_e32 v19, 32, v19
	v_lshlrev_b64 v[24:25], v19, v[24:25]
	v_min_u32_e32 v21, 1, v24
	v_or_b32_e32 v21, v25, v21
	v_cvt_f32_u32_e32 v21, v21
	v_sub_u32_e32 v19, 32, v19
	v_lshlrev_b64 v[24:25], 7, v[30:31]
	v_lshl_add_u64 v[24:25], v[0:1], 0, v[24:25]
	v_ldexp_f32 v19, v21, v19
	v_mul_f32_e32 v19, 0x33800000, v19
	v_fmamk_f32 v19, v19, 0x3a000000, v209
	v_rsq_f32_e32 v19, v19
	v_ashrrev_i32_e32 v21, 31, v20
	v_fma_f32 v12, v12, v19, 0
	global_store_dword v[24:25], v12, off
	v_ffbh_u32_e32 v12, v27
	v_min_u32_e32 v12, 32, v12
	v_lshlrev_b64 v[26:27], v12, v[26:27]
	v_min_u32_e32 v23, 1, v26
	v_or_b32_e32 v23, v27, v23
	v_cvt_f32_u32_e32 v23, v23
	v_sub_u32_e32 v12, 32, v12
	v_fma_f32 v2, v8, v19, 0
	global_store_dword v[24:25], v2, off offset:64
	v_ldexp_f32 v12, v23, v12
	v_mul_f32_e32 v12, 0x33800000, v12
	v_fmamk_f32 v12, v12, 0x3a000000, v209
	v_rsq_f32_e32 v23, v12
	s_nop 0
	v_fma_f32 v26, v13, v23, 0
	v_lshlrev_b64 v[12:13], 7, v[20:21]
	v_lshl_add_u64 v[12:13], v[0:1], 0, v[12:13]
	v_fma_f32 v2, v9, v23, 0
	global_store_dword v[12:13], v26, off
	global_store_dword v[12:13], v2, off offset:64
	s_cbranch_scc0 .LBB0_380

; DI f32x4 mfma16(bf16x8 a, bf16x8 b, f32x4 c) { return __builtin_amdgcn_mfma_f32_16x16x32_bf16(a, b, c, 0, 0, 0); }
; DI void s5_end_gemm(const Ctx& C, const bf16* PROJ, const bf16* G, float* ENDF) {
;     ...
;         const bf16* ap = PROJ + ((size_t)g * T + ab * SEQ + as * SSEG) * 16 + 8 * fq;
;         const bf16* bp = G + ((size_t)gd * 128 + nh * 64 + fr) * 2048 + 8 * fq;
;         f32x4 acc[4];
; #pragma unroll
;         for (int ct = 0; ct < 4; ++ct) acc[ct] = (f32x4){0.f, 0.f, 0.f, 0.f};
; #pragma unroll 4
;         for (int ks = 0; ks < 64; ++ks) { const bf16x8 a = *(const bf16x8*)(ap + 32 * ks);
; #pragma unroll
;             for (int ct = 0; ct < 4; ++ct) acc[ct] = mfma16(a, *(const bf16x8*)(bp + (size_t)ct * 16 * 2048 + 32 * ks), acc[ct]); }
; #pragma unroll
;         for (int ct = 0; ct < 4; ++ct)
; #pragma unroll
;             for (int j = 0; j < 4; ++j) { const int r = 16 * w + fq * 4 + j, b = r >> 6, s = r & 63, sl = dir ? SNSEG - 1 - s : s;
;                 ENDF[((size_t)((b * 2 + dir) * SNSEG + sl)) * 8192 + g * 128 + nh * 64 + ct * 16 + fr] = acc[ct][j]; }
.LBB0_525:
	v_lshl_add_u64 v[38:39], v[28:29], 0, s[8:9]
	v_add_co_u32_e32 v46, vcc, s82, v38
	v_lshl_add_u64 v[48:49], v[26:27], 0, s[8:9]
	s_nop 0
	v_addc_co_u32_e32 v47, vcc, 0, v39, vcc
	s_mov_b32 s1, 0x27000000
	v_add_co_u32_e32 v50, vcc, s1, v48
	s_mov_b32 s1, 0x27010000
	s_nop 0
	v_addc_co_u32_e32 v51, vcc, 0, v49, vcc
	v_add_co_u32_e32 v52, vcc, s1, v48
	s_mov_b32 s1, 0x27020000
	s_nop 0
	v_addc_co_u32_e32 v53, vcc, 0, v49, vcc
	v_add_co_u32_e32 v54, vcc, s1, v48
	s_mov_b32 s1, 0x27030000
	s_nop 0
	v_addc_co_u32_e32 v55, vcc, 0, v49, vcc
	v_add_co_u32_e32 v48, vcc, s1, v48
	s_add_u32 s8, s8, 0x100
	s_nop 0
	v_addc_co_u32_e32 v49, vcc, 0, v49, vcc
	s_addc_u32 s9, s9, 0
	s_cmpk_eq_i32 s8, 0x1000
	global_load_dwordx4 v[80:83], v[46:47], off
	global_load_dwordx4 v[96:99], v[50:51], off
	global_load_dwordx4 v[100:103], v[52:53], off
	global_load_dwordx4 v[104:107], v[54:55], off
	global_load_dwordx4 v[108:111], v[48:49], off
	global_load_dwordx4 v[84:87], v[46:47], off offset:64
	global_load_dwordx4 v[112:115], v[50:51], off offset:64
	global_load_dwordx4 v[116:119], v[52:53], off offset:64
	global_load_dwordx4 v[120:123], v[54:55], off offset:64
	global_load_dwordx4 v[124:127], v[48:49], off offset:64
	global_load_dwordx4 v[88:91], v[46:47], off offset:128
	global_load_dwordx4 v[128:131], v[50:51], off offset:128
	global_load_dwordx4 v[132:135], v[52:53], off offset:128
	global_load_dwordx4 v[136:139], v[54:55], off offset:128
	global_load_dwordx4 v[140:143], v[48:49], off offset:128
	global_load_dwordx4 v[92:95], v[46:47], off offset:192
	global_load_dwordx4 v[164:167], v[50:51], off offset:192
	global_load_dwordx4 v[168:171], v[52:53], off offset:192
	global_load_dwordx4 v[172:175], v[54:55], off offset:192
	global_load_dwordx4 v[176:179], v[48:49], off offset:192
	s_waitcnt vmcnt(18) lgkmcnt(0)
	v_mfma_f32_16x16x32_bf16 v[18:21], v[80:83], v[96:99], v[18:21]
	s_waitcnt vmcnt(17)
	v_mfma_f32_16x16x32_bf16 v[14:17], v[80:83], v[100:103], v[14:17]
	s_waitcnt vmcnt(16)
	v_mfma_f32_16x16x32_bf16 v[10:13], v[80:83], v[104:107], v[10:13]
	s_waitcnt vmcnt(15)
	v_mfma_f32_16x16x32_bf16 v[6:9], v[80:83], v[108:111], v[6:9]
	s_waitcnt vmcnt(13)
	v_mfma_f32_16x16x32_bf16 v[18:21], v[84:87], v[112:115], v[18:21]
	s_waitcnt vmcnt(12)
	v_mfma_f32_16x16x32_bf16 v[14:17], v[84:87], v[116:119], v[14:17]
	s_waitcnt vmcnt(11)
	v_mfma_f32_16x16x32_bf16 v[10:13], v[84:87], v[120:123], v[10:13]
	s_waitcnt vmcnt(10)
	v_mfma_f32_16x16x32_bf16 v[6:9], v[84:87], v[124:127], v[6:9]
	s_waitcnt vmcnt(8)
	v_mfma_f32_16x16x32_bf16 v[18:21], v[88:91], v[128:131], v[18:21]
	s_waitcnt vmcnt(7)
	v_mfma_f32_16x16x32_bf16 v[14:17], v[88:91], v[132:135], v[14:17]
	s_waitcnt vmcnt(6)
	v_mfma_f32_16x16x32_bf16 v[10:13], v[88:91], v[136:139], v[10:13]
	s_waitcnt vmcnt(5)
	v_mfma_f32_16x16x32_bf16 v[6:9], v[88:91], v[140:143], v[6:9]
	s_waitcnt vmcnt(3)
	v_mfma_f32_16x16x32_bf16 v[18:21], v[92:95], v[164:167], v[18:21]
	s_waitcnt vmcnt(2)
	v_mfma_f32_16x16x32_bf16 v[14:17], v[92:95], v[168:171], v[14:17]
	s_waitcnt vmcnt(1)
	v_mfma_f32_16x16x32_bf16 v[10:13], v[92:95], v[172:175], v[10:13]
	s_waitcnt vmcnt(0)
	v_mfma_f32_16x16x32_bf16 v[6:9], v[92:95], v[176:179], v[6:9]
	s_cbranch_scc0 .LBB0_525
	s_bfe_u32 s1, s14, 0x10001
	s_cmp_eq_u32 s1, 0
	s_cselect_b64 vcc, -1, 0
	s_or_b32 s1, s1, s12
	s_lshl_b32 s0, s0, 7
	s_lshl_b32 s8, s1, 6
	s_ashr_i32 s1, s0, 31
	s_lshl_b64 s[0:1], s[0:1], 2
	s_add_u32 s0, s10, s0
	s_addc_u32 s1, s11, s1
	s_lshl_b32 s9, s14, 8
	v_cndmask_b32_e32 v28, v31, v30, vcc
	s_and_b32 s9, s9, 0x100
	s_add_u32 s0, s0, s9
	v_or_b32_e32 v28, s8, v28
	s_addc_u32 s1, s1, 0
	v_ashrrev_i32_e32 v29, 31, v28
	v_lshl_add_u64 v[26:27], s[0:1], 0, v[2:3]
	v_lshlrev_b64 v[28:29], 15, v[28:29]
	v_lshl_add_u64 v[28:29], v[26:27], 0, v[28:29]
	global_store_dword v[28:29], v18, off
	v_cndmask_b32_e32 v18, v33, v32, vcc
	v_or_b32_e32 v38, s8, v18
	v_ashrrev_i32_e32 v39, 31, v38
	v_lshlrev_b64 v[38:39], 15, v[38:39]
	v_cndmask_b32_e32 v18, v35, v34, vcc
	v_lshl_add_u64 v[38:39], v[26:27], 0, v[38:39]
	v_or_b32_e32 v18, s8, v18
	global_store_dword v[38:39], v19, off
	v_ashrrev_i32_e32 v19, 31, v18
	v_lshlrev_b64 v[18:19], 15, v[18:19]
	v_lshl_add_u64 v[18:19], v[26:27], 0, v[18:19]
	global_store_dword v[18:19], v20, off
	v_cndmask_b32_e32 v20, v37, v36, vcc
	v_or_b32_e32 v40, s8, v20
	v_ashrrev_i32_e32 v41, 31, v40
	v_readlane_b32 s0, v254, 45
	v_lshlrev_b64 v[40:41], 15, v[40:41]
	s_add_i32 s14, s14, s62
	s_add_i32 s13, s13, s0
	v_lshl_add_u64 v[26:27], v[26:27], 0, v[40:41]
	s_cmpk_gt_i32 s14, 0xff
	global_store_dword v[26:27], v21, off
	global_store_dword v[28:29], v14, off offset:64
	global_store_dword v[38:39], v15, off offset:64
	global_store_dword v[18:19], v16, off offset:64
	global_store_dword v[26:27], v17, off offset:64
	global_store_dword v[28:29], v10, off offset:128
	global_store_dword v[38:39], v11, off offset:128
	global_store_dword v[18:19], v12, off offset:128
	global_store_dword v[26:27], v13, off offset:128
	global_store_dword v[28:29], v6, off offset:192
	global_store_dword v[38:39], v7, off offset:192
	global_store_dword v[18:19], v8, off offset:192
	global_store_dword v[26:27], v9, off offset:192
	s_cbranch_scc0 .LBB0_524

; template <int DIRN> DI void s5_dir(const S5P& P, const f32x2* END, const LAS float* UF, LAS bf16* XT, int b, int seg, int g, const bf16x8 (&bfr)[4], f32x4 (&acc)[8], int lane) {
;     ...
;     { float Lr = lr, Li = li;
; #pragma unroll
;         for (int i = 0; i < 7; ++i) { const float nr = Lr * Lr - Li * Li, ni = 2.0f * Lr * Li; Lr = nr; Li = ni; }
; #pragma unroll 8
;         for (int j = 0; j < sl; ++j) { const float* ep = (const float*)END + ((size_t)((b * 2 + DIRN) * SNSEG + j)) * 8192 + g * 128 + lane; const f32x2 e = {ep[0], ep[64]}; const float nr = Lr * xr - Li * xi + e.x, ni = Lr * xi + Li * xr + e.y; xr = nr; xi = ni; } }
.LBB0_617:
	global_load_dword v184, v[80:81], off
	global_load_dword v185, v[80:81], off offset:256
	v_add_co_u32_e32 v80, vcc, 0x8000, v80
	s_nop 1
	v_addc_co_u32_e32 v81, vcc, 0, v81, vcc
	global_load_dword v186, v[80:81], off
	global_load_dword v187, v[80:81], off offset:256
	v_add_co_u32_e32 v80, vcc, 0x8000, v80
	s_nop 1
	v_addc_co_u32_e32 v81, vcc, 0, v81, vcc
	global_load_dword v188, v[80:81], off
	global_load_dword v189, v[80:81], off offset:256
	v_add_co_u32_e32 v80, vcc, 0x8000, v80
	s_nop 1
	v_addc_co_u32_e32 v81, vcc, 0, v81, vcc
	global_load_dword v190, v[80:81], off
	global_load_dword v191, v[80:81], off offset:256
	v_add_co_u32_e32 v80, vcc, 0x8000, v80
	s_nop 1
	v_addc_co_u32_e32 v81, vcc, 0, v81, vcc
	global_load_dword v192, v[80:81], off
	global_load_dword v193, v[80:81], off offset:256
	v_add_co_u32_e32 v80, vcc, 0x8000, v80
	s_nop 1
	v_addc_co_u32_e32 v81, vcc, 0, v81, vcc
	global_load_dword v194, v[80:81], off
	global_load_dword v195, v[80:81], off offset:256
	v_add_co_u32_e32 v80, vcc, 0x8000, v80
	s_nop 1
	v_addc_co_u32_e32 v81, vcc, 0, v81, vcc
	global_load_dword v196, v[80:81], off
	global_load_dword v197, v[80:81], off offset:256
	v_add_co_u32_e32 v80, vcc, 0x8000, v80
	s_nop 1
	v_addc_co_u32_e32 v81, vcc, 0, v81, vcc
	global_load_dword v198, v[80:81], off
	global_load_dword v199, v[80:81], off offset:256
	v_add_co_u32_e32 v80, vcc, 0x8000, v80
	s_nop 1
	v_addc_co_u32_e32 v81, vcc, 0, v81, vcc
	s_add_i32 s1, s1, 8
	v_pk_mul_f32 v[84:85], v[74:75], v[174:175] op_sel:[0,1] op_sel_hi:[1,0]
	s_nop 0
	v_pk_fma_f32 v[88:89], v[76:77], v[174:175], v[84:85]
	v_pk_fma_f32 v[82:83], v[76:77], v[174:175], v[84:85] neg_lo:[0,0,1] neg_hi:[0,0,1]
	s_nop 0
	v_mov_b32_e32 v83, v89
	s_waitcnt vmcnt(14) lgkmcnt(0)
	v_pk_add_f32 v[174:175], v[82:83], v[184:185]
	v_pk_mul_f32 v[84:85], v[74:75], v[174:175] op_sel:[0,1] op_sel_hi:[1,0]
	s_nop 0
	v_pk_fma_f32 v[88:89], v[76:77], v[174:175], v[84:85]
	v_pk_fma_f32 v[82:83], v[76:77], v[174:175], v[84:85] neg_lo:[0,0,1] neg_hi:[0,0,1]
	s_nop 0
	v_mov_b32_e32 v83, v89
	s_waitcnt vmcnt(12)
	v_pk_add_f32 v[174:175], v[82:83], v[186:187]
	v_pk_mul_f32 v[84:85], v[74:75], v[174:175] op_sel:[0,1] op_sel_hi:[1,0]
	s_nop 0
	v_pk_fma_f32 v[88:89], v[76:77], v[174:175], v[84:85]
	v_pk_fma_f32 v[82:83], v[76:77], v[174:175], v[84:85] neg_lo:[0,0,1] neg_hi:[0,0,1]
	s_nop 0
	v_mov_b32_e32 v83, v89
	s_waitcnt vmcnt(10)
	v_pk_add_f32 v[174:175], v[82:83], v[188:189]
	v_pk_mul_f32 v[84:85], v[74:75], v[174:175] op_sel:[0,1] op_sel_hi:[1,0]
	s_nop 0
	v_pk_fma_f32 v[88:89], v[76:77], v[174:175], v[84:85]
	v_pk_fma_f32 v[82:83], v[76:77], v[174:175], v[84:85] neg_lo:[0,0,1] neg_hi:[0,0,1]
	s_nop 0
	v_mov_b32_e32 v83, v89
	s_waitcnt vmcnt(8)
	v_pk_add_f32 v[174:175], v[82:83], v[190:191]
	v_pk_mul_f32 v[84:85], v[74:75], v[174:175] op_sel:[0,1] op_sel_hi:[1,0]
	s_nop 0
	v_pk_fma_f32 v[88:89], v[76:77], v[174:175], v[84:85]
	v_pk_fma_f32 v[82:83], v[76:77], v[174:175], v[84:85] neg_lo:[0,0,1] neg_hi:[0,0,1]
	s_nop 0
	v_mov_b32_e32 v83, v89
	s_waitcnt vmcnt(6)
	v_pk_add_f32 v[174:175], v[82:83], v[192:193]
	v_pk_mul_f32 v[84:85], v[74:75], v[174:175] op_sel:[0,1] op_sel_hi:[1,0]
	s_nop 0
	v_pk_fma_f32 v[88:89], v[76:77], v[174:175], v[84:85]
	v_pk_fma_f32 v[82:83], v[76:77], v[174:175], v[84:85] neg_lo:[0,0,1] neg_hi:[0,0,1]
	s_nop 0
	v_mov_b32_e32 v83, v89
	s_waitcnt vmcnt(4)
	v_pk_add_f32 v[174:175], v[82:83], v[194:195]
	v_pk_mul_f32 v[84:85], v[74:75], v[174:175] op_sel:[0,1] op_sel_hi:[1,0]
	s_nop 0
	v_pk_fma_f32 v[88:89], v[76:77], v[174:175], v[84:85]
	v_pk_fma_f32 v[82:83], v[76:77], v[174:175], v[84:85] neg_lo:[0,0,1] neg_hi:[0,0,1]
	s_nop 0
	v_mov_b32_e32 v83, v89
	s_waitcnt vmcnt(2)
	v_pk_add_f32 v[174:175], v[82:83], v[196:197]
	v_pk_mul_f32 v[84:85], v[74:75], v[174:175] op_sel:[0,1] op_sel_hi:[1,0]
	s_nop 0
	v_pk_fma_f32 v[88:89], v[76:77], v[174:175], v[84:85]
	v_pk_fma_f32 v[82:83], v[76:77], v[174:175], v[84:85] neg_lo:[0,0,1] neg_hi:[0,0,1]
	s_nop 0
	v_mov_b32_e32 v83, v89
	s_waitcnt vmcnt(0)
	v_pk_add_f32 v[174:175], v[82:83], v[198:199]
	s_cmp_eq_u32 s11, s1
	s_cbranch_scc0 .LBB0_617
	s_bfe_u32 s1, s30, 0x30006
	s_cmp_eq_u32 s1, 0
	s_cbranch_scc0 .LBB0_620
	s_branch .LBB0_622

; template <int DIRN> DI void s5_dir(const S5P& P, const f32x2* END, const LAS float* UF, LAS bf16* XT, int b, int seg, int g, const bf16x8 (&bfr)[4], f32x4 (&acc)[8], int lane) {
;     ...
;     { float Lr = lr, Li = li;
; #pragma unroll
;         for (int i = 0; i < 7; ++i) { const float nr = Lr * Lr - Li * Li, ni = 2.0f * Lr * Li; Lr = nr; Li = ni; }
; #pragma unroll 8
;         for (int j = 0; j < sl; ++j) { const float* ep = (const float*)END + ((size_t)((b * 2 + DIRN) * SNSEG + j)) * 8192 + g * 128 + lane; const f32x2 e = {ep[0], ep[64]}; const float nr = Lr * xr - Li * xi + e.x, ni = Lr * xi + Li * xr + e.y; xr = nr; xi = ni; } }
;     f32x2 x = {xr, xi};
.LBB0_640:
.LBB0_641:
	s_xor_b32 s10, s69, 63
	s_add_i32 s0, s8, 64
	s_ashr_i32 s1, s0, 31
	s_lshl_b64 s[0:1], s[0:1], 15
	v_lshl_add_u64 v[200:201], v[98:99], 0, s[0:1]
.Ls5p1_blk_a:
	s_sub_i32 s0, s10, s9
	s_cmp_lt_i32 s0, 8
	s_cbranch_scc1 .Ls5p1_rem_a
	global_load_dword v184, v[200:201], off
	global_load_dword v185, v[200:201], off offset:256
	v_add_co_u32_e32 v200, vcc, 0x8000, v200
	s_nop 1
	v_addc_co_u32_e32 v201, vcc, 0, v201, vcc
	global_load_dword v186, v[200:201], off
	global_load_dword v187, v[200:201], off offset:256
	v_add_co_u32_e32 v200, vcc, 0x8000, v200
	s_nop 1
	v_addc_co_u32_e32 v201, vcc, 0, v201, vcc
	global_load_dword v188, v[200:201], off
	global_load_dword v189, v[200:201], off offset:256
	v_add_co_u32_e32 v200, vcc, 0x8000, v200
	s_nop 1
	v_addc_co_u32_e32 v201, vcc, 0, v201, vcc
	global_load_dword v190, v[200:201], off
	global_load_dword v191, v[200:201], off offset:256
	v_add_co_u32_e32 v200, vcc, 0x8000, v200
	s_nop 1
	v_addc_co_u32_e32 v201, vcc, 0, v201, vcc
	global_load_dword v192, v[200:201], off
	global_load_dword v193, v[200:201], off offset:256
	v_add_co_u32_e32 v200, vcc, 0x8000, v200
	s_nop 1
	v_addc_co_u32_e32 v201, vcc, 0, v201, vcc
	global_load_dword v194, v[200:201], off
	global_load_dword v195, v[200:201], off offset:256
	v_add_co_u32_e32 v200, vcc, 0x8000, v200
	s_nop 1
	v_addc_co_u32_e32 v201, vcc, 0, v201, vcc
	global_load_dword v196, v[200:201], off
	global_load_dword v197, v[200:201], off offset:256
	v_add_co_u32_e32 v200, vcc, 0x8000, v200
	s_nop 1
	v_addc_co_u32_e32 v201, vcc, 0, v201, vcc
	global_load_dword v198, v[200:201], off
	global_load_dword v199, v[200:201], off offset:256
	v_add_co_u32_e32 v200, vcc, 0x8000, v200
	s_nop 1
	v_addc_co_u32_e32 v201, vcc, 0, v201, vcc
	v_pk_mul_f32 v[100:101], v[94:95], v[90:91]
	s_nop 0
	v_pk_fma_f32 v[104:105], v[96:97], v[90:91], v[100:101] op_sel:[0,0,1] op_sel_hi:[1,1,0] neg_lo:[0,0,1] neg_hi:[0,0,1]
	v_pk_fma_f32 v[90:91], v[96:97], v[90:91], v[100:101] op_sel:[0,0,1] op_sel_hi:[1,1,0]
	s_nop 0
	v_mov_b32_e32 v105, v91
	s_waitcnt vmcnt(14) lgkmcnt(0)
	v_pk_add_f32 v[90:91], v[104:105], v[184:185]
	v_pk_mul_f32 v[100:101], v[94:95], v[90:91]
	s_nop 0
	v_pk_fma_f32 v[104:105], v[96:97], v[90:91], v[100:101] op_sel:[0,0,1] op_sel_hi:[1,1,0] neg_lo:[0,0,1] neg_hi:[0,0,1]
	v_pk_fma_f32 v[90:91], v[96:97], v[90:91], v[100:101] op_sel:[0,0,1] op_sel_hi:[1,1,0]
	s_nop 0
	v_mov_b32_e32 v105, v91
	s_waitcnt vmcnt(12)
	v_pk_add_f32 v[90:91], v[104:105], v[186:187]
	v_pk_mul_f32 v[100:101], v[94:95], v[90:91]
	s_nop 0
	v_pk_fma_f32 v[104:105], v[96:97], v[90:91], v[100:101] op_sel:[0,0,1] op_sel_hi:[1,1,0] neg_lo:[0,0,1] neg_hi:[0,0,1]
	v_pk_fma_f32 v[90:91], v[96:97], v[90:91], v[100:101] op_sel:[0,0,1] op_sel_hi:[1,1,0]
	s_nop 0
	v_mov_b32_e32 v105, v91
	s_waitcnt vmcnt(10)
	v_pk_add_f32 v[90:91], v[104:105], v[188:189]
	v_pk_mul_f32 v[100:101], v[94:95], v[90:91]
	s_nop 0
	v_pk_fma_f32 v[104:105], v[96:97], v[90:91], v[100:101] op_sel:[0,0,1] op_sel_hi:[1,1,0] neg_lo:[0,0,1] neg_hi:[0,0,1]
	v_pk_fma_f32 v[90:91], v[96:97], v[90:91], v[100:101] op_sel:[0,0,1] op_sel_hi:[1,1,0]
	s_nop 0
	v_mov_b32_e32 v105, v91
	s_waitcnt vmcnt(8)
	v_pk_add_f32 v[90:91], v[104:105], v[190:191]
	v_pk_mul_f32 v[100:101], v[94:95], v[90:91]
	s_nop 0
	v_pk_fma_f32 v[104:105], v[96:97], v[90:91], v[100:101] op_sel:[0,0,1] op_sel_hi:[1,1,0] neg_lo:[0,0,1] neg_hi:[0,0,1]
	v_pk_fma_f32 v[90:91], v[96:97], v[90:91], v[100:101] op_sel:[0,0,1] op_sel_hi:[1,1,0]
	s_nop 0
	v_mov_b32_e32 v105, v91
	s_waitcnt vmcnt(6)
	v_pk_add_f32 v[90:91], v[104:105], v[192:193]
	v_pk_mul_f32 v[100:101], v[94:95], v[90:91]
	s_nop 0
	v_pk_fma_f32 v[104:105], v[96:97], v[90:91], v[100:101] op_sel:[0,0,1] op_sel_hi:[1,1,0] neg_lo:[0,0,1] neg_hi:[0,0,1]
	v_pk_fma_f32 v[90:91], v[96:97], v[90:91], v[100:101] op_sel:[0,0,1] op_sel_hi:[1,1,0]
	s_nop 0
	v_mov_b32_e32 v105, v91
	s_waitcnt vmcnt(4)
	v_pk_add_f32 v[90:91], v[104:105], v[194:195]
	v_pk_mul_f32 v[100:101], v[94:95], v[90:91]
	s_nop 0
	v_pk_fma_f32 v[104:105], v[96:97], v[90:91], v[100:101] op_sel:[0,0,1] op_sel_hi:[1,1,0] neg_lo:[0,0,1] neg_hi:[0,0,1]
	v_pk_fma_f32 v[90:91], v[96:97], v[90:91], v[100:101] op_sel:[0,0,1] op_sel_hi:[1,1,0]
	s_nop 0
	v_mov_b32_e32 v105, v91
	s_waitcnt vmcnt(2)
	v_pk_add_f32 v[90:91], v[104:105], v[196:197]
	v_pk_mul_f32 v[100:101], v[94:95], v[90:91]
	s_nop 0
	v_pk_fma_f32 v[104:105], v[96:97], v[90:91], v[100:101] op_sel:[0,0,1] op_sel_hi:[1,1,0] neg_lo:[0,0,1] neg_hi:[0,0,1]
	v_pk_fma_f32 v[90:91], v[96:97], v[90:91], v[100:101] op_sel:[0,0,1] op_sel_hi:[1,1,0]
	s_nop 0
	v_mov_b32_e32 v105, v91
	s_waitcnt vmcnt(0)
	v_pk_add_f32 v[90:91], v[104:105], v[198:199]
	s_add_i32 s9, s9, 8
	s_branch .Ls5p1_blk_a
.Ls5p1_rem_a:
	s_cmp_eq_u32 s0, 0
	s_cbranch_scc1 .LBB0_650
.Ls5p1_reml_a:
	global_load_dword v184, v[200:201], off
	global_load_dword v185, v[200:201], off offset:256
	v_add_co_u32_e32 v200, vcc, 0x8000, v200
	s_nop 1
	v_addc_co_u32_e32 v201, vcc, 0, v201, vcc
	v_pk_mul_f32 v[100:101], v[94:95], v[90:91]
	s_nop 0
	v_pk_fma_f32 v[104:105], v[96:97], v[90:91], v[100:101] op_sel:[0,0,1] op_sel_hi:[1,1,0] neg_lo:[0,0,1] neg_hi:[0,0,1]
	v_pk_fma_f32 v[90:91], v[96:97], v[90:91], v[100:101] op_sel:[0,0,1] op_sel_hi:[1,1,0]
	s_nop 0
	v_mov_b32_e32 v105, v91
	s_waitcnt vmcnt(0) lgkmcnt(0)
	v_pk_add_f32 v[90:91], v[104:105], v[184:185]
	s_add_i32 s0, s0, -1
	s_cmp_lg_u32 s0, 0
	s_cbranch_scc1 .Ls5p1_reml_a
	s_branch .LBB0_650

; template <int DIRN> DI void s5_dir(const S5P& P, const f32x2* END, const LAS float* UF, LAS bf16* XT, int b, int seg, int g, const bf16x8 (&bfr)[4], f32x4 (&acc)[8], int lane) {
;     ...
;     { float Lr = lr, Li = li;
; #pragma unroll
;         for (int i = 0; i < 7; ++i) { const float nr = Lr * Lr - Li * Li, ni = 2.0f * Lr * Li; Lr = nr; Li = ni; }
; #pragma unroll 8
;         for (int j = 0; j < sl; ++j) { const float* ep = (const float*)END + ((size_t)((b * 2 + DIRN) * SNSEG + j)) * 8192 + g * 128 + lane; const f32x2 e = {ep[0], ep[64]}; const float nr = Lr * xr - Li * xi + e.x, ni = Lr * xi + Li * xr + e.y; xr = nr; xi = ni; } }
.LBB0_691:
	global_load_dword v184, v[80:81], off
	global_load_dword v185, v[80:81], off offset:256
	v_add_co_u32_e32 v80, vcc, 0x8000, v80
	s_nop 1
	v_addc_co_u32_e32 v81, vcc, 0, v81, vcc
	global_load_dword v186, v[80:81], off
	global_load_dword v187, v[80:81], off offset:256
	v_add_co_u32_e32 v80, vcc, 0x8000, v80
	s_nop 1
	v_addc_co_u32_e32 v81, vcc, 0, v81, vcc
	global_load_dword v188, v[80:81], off
	global_load_dword v189, v[80:81], off offset:256
	v_add_co_u32_e32 v80, vcc, 0x8000, v80
	s_nop 1
	v_addc_co_u32_e32 v81, vcc, 0, v81, vcc
	global_load_dword v190, v[80:81], off
	global_load_dword v191, v[80:81], off offset:256
	v_add_co_u32_e32 v80, vcc, 0x8000, v80
	s_nop 1
	v_addc_co_u32_e32 v81, vcc, 0, v81, vcc
	global_load_dword v192, v[80:81], off
	global_load_dword v193, v[80:81], off offset:256
	v_add_co_u32_e32 v80, vcc, 0x8000, v80
	s_nop 1
	v_addc_co_u32_e32 v81, vcc, 0, v81, vcc
	global_load_dword v194, v[80:81], off
	global_load_dword v195, v[80:81], off offset:256
	v_add_co_u32_e32 v80, vcc, 0x8000, v80
	s_nop 1
	v_addc_co_u32_e32 v81, vcc, 0, v81, vcc
	global_load_dword v196, v[80:81], off
	global_load_dword v197, v[80:81], off offset:256
	v_add_co_u32_e32 v80, vcc, 0x8000, v80
	s_nop 1
	v_addc_co_u32_e32 v81, vcc, 0, v81, vcc
	global_load_dword v198, v[80:81], off
	global_load_dword v199, v[80:81], off offset:256
	v_add_co_u32_e32 v80, vcc, 0x8000, v80
	s_nop 1
	v_addc_co_u32_e32 v81, vcc, 0, v81, vcc
	s_add_i32 s1, s1, 8
	v_pk_mul_f32 v[84:85], v[74:75], v[172:173] op_sel:[0,1] op_sel_hi:[1,0]
	s_nop 0
	v_pk_fma_f32 v[88:89], v[76:77], v[172:173], v[84:85]
	v_pk_fma_f32 v[82:83], v[76:77], v[172:173], v[84:85] neg_lo:[0,0,1] neg_hi:[0,0,1]
	s_nop 0
	v_mov_b32_e32 v83, v89
	s_waitcnt vmcnt(14) lgkmcnt(0)
	v_pk_add_f32 v[172:173], v[82:83], v[184:185]
	v_pk_mul_f32 v[84:85], v[74:75], v[172:173] op_sel:[0,1] op_sel_hi:[1,0]
	s_nop 0
	v_pk_fma_f32 v[88:89], v[76:77], v[172:173], v[84:85]
	v_pk_fma_f32 v[82:83], v[76:77], v[172:173], v[84:85] neg_lo:[0,0,1] neg_hi:[0,0,1]
	s_nop 0
	v_mov_b32_e32 v83, v89
	s_waitcnt vmcnt(12)
	v_pk_add_f32 v[172:173], v[82:83], v[186:187]
	v_pk_mul_f32 v[84:85], v[74:75], v[172:173] op_sel:[0,1] op_sel_hi:[1,0]
	s_nop 0
	v_pk_fma_f32 v[88:89], v[76:77], v[172:173], v[84:85]
	v_pk_fma_f32 v[82:83], v[76:77], v[172:173], v[84:85] neg_lo:[0,0,1] neg_hi:[0,0,1]
	s_nop 0
	v_mov_b32_e32 v83, v89
	s_waitcnt vmcnt(10)
	v_pk_add_f32 v[172:173], v[82:83], v[188:189]
	v_pk_mul_f32 v[84:85], v[74:75], v[172:173] op_sel:[0,1] op_sel_hi:[1,0]
	s_nop 0
	v_pk_fma_f32 v[88:89], v[76:77], v[172:173], v[84:85]
	v_pk_fma_f32 v[82:83], v[76:77], v[172:173], v[84:85] neg_lo:[0,0,1] neg_hi:[0,0,1]
	s_nop 0
	v_mov_b32_e32 v83, v89
	s_waitcnt vmcnt(8)
	v_pk_add_f32 v[172:173], v[82:83], v[190:191]
	v_pk_mul_f32 v[84:85], v[74:75], v[172:173] op_sel:[0,1] op_sel_hi:[1,0]
	s_nop 0
	v_pk_fma_f32 v[88:89], v[76:77], v[172:173], v[84:85]
	v_pk_fma_f32 v[82:83], v[76:77], v[172:173], v[84:85] neg_lo:[0,0,1] neg_hi:[0,0,1]
	s_nop 0
	v_mov_b32_e32 v83, v89
	s_waitcnt vmcnt(6)
	v_pk_add_f32 v[172:173], v[82:83], v[192:193]
	v_pk_mul_f32 v[84:85], v[74:75], v[172:173] op_sel:[0,1] op_sel_hi:[1,0]
	s_nop 0
	v_pk_fma_f32 v[88:89], v[76:77], v[172:173], v[84:85]
	v_pk_fma_f32 v[82:83], v[76:77], v[172:173], v[84:85] neg_lo:[0,0,1] neg_hi:[0,0,1]
	s_nop 0
	v_mov_b32_e32 v83, v89
	s_waitcnt vmcnt(4)
	v_pk_add_f32 v[172:173], v[82:83], v[194:195]
	v_pk_mul_f32 v[84:85], v[74:75], v[172:173] op_sel:[0,1] op_sel_hi:[1,0]
	s_nop 0
	v_pk_fma_f32 v[88:89], v[76:77], v[172:173], v[84:85]
	v_pk_fma_f32 v[82:83], v[76:77], v[172:173], v[84:85] neg_lo:[0,0,1] neg_hi:[0,0,1]
	s_nop 0
	v_mov_b32_e32 v83, v89
	s_waitcnt vmcnt(2)
	v_pk_add_f32 v[172:173], v[82:83], v[196:197]
	v_pk_mul_f32 v[84:85], v[74:75], v[172:173] op_sel:[0,1] op_sel_hi:[1,0]
	s_nop 0
	v_pk_fma_f32 v[88:89], v[76:77], v[172:173], v[84:85]
	v_pk_fma_f32 v[82:83], v[76:77], v[172:173], v[84:85] neg_lo:[0,0,1] neg_hi:[0,0,1]
	s_nop 0
	v_mov_b32_e32 v83, v89
	s_waitcnt vmcnt(0)
	v_pk_add_f32 v[172:173], v[82:83], v[198:199]
	s_cmp_eq_u32 s11, s1
	s_cbranch_scc0 .LBB0_691
	s_bfe_u32 s1, s54, 0x30006
	s_cmp_eq_u32 s1, 0
	s_cbranch_scc0 .LBB0_694
	s_branch .LBB0_696

; template <int DIRN> DI void s5_dir(const S5P& P, const f32x2* END, const LAS float* UF, LAS bf16* XT, int b, int seg, int g, const bf16x8 (&bfr)[4], f32x4 (&acc)[8], int lane) {
;     ...
;     const int sl = DIRN ? SNSEG - 1 - seg : seg; float xr = 0.f, xi = 0.f;
;     { float Lr = lr, Li = li;
; #pragma unroll
;         for (int i = 0; i < 7; ++i) { const float nr = Lr * Lr - Li * Li, ni = 2.0f * Lr * Li; Lr = nr; Li = ni; }
; #pragma unroll 8
;         for (int j = 0; j < sl; ++j) { const float* ep = (const float*)END + ((size_t)((b * 2 + DIRN) * SNSEG + j)) * 8192 + g * 128 + lane; const f32x2 e = {ep[0], ep[64]}; const float nr = Lr * xr - Li * xi + e.x, ni = Lr * xi + Li * xr + e.y; xr = nr; xi = ni; } }
.LBB0_714:
.LBB0_715:
	s_xor_b32 s10, s53, 63
	s_add_i32 s0, s8, 64
	s_ashr_i32 s1, s0, 31
	s_lshl_b64 s[0:1], s[0:1], 15
	v_lshl_add_u64 v[200:201], v[98:99], 0, s[0:1]

; __device__ __forceinline__ float ep_rstd(const rowss_t* rowss, int row) { return __builtin_amdgcn_rsqf((float)rowss[row] * (1.0f / 16777216.0f) * (1.0f / 2048.0f) + 1e-6f); }
; DI f32x4 mfma16(bf16x8 a, bf16x8 b, f32x4 c) { return __builtin_amdgcn_mfma_f32_16x16x32_bf16(a, b, c, 0, 0, 0); }
; template <int NT> DI void gate_gemm(const Ctx& C, const bf16* HN, const bf16* WgT, const float* bias, float* G, const pg8::rowss_t* rowss) {
;     ...
;         const bf16* a = HN + (size_t)(rt * 16 + (lane & 15)) * D + (lane >> 4) * 8;
;         const bf16* b = WgT + (size_t)(lane & 15) * D + (lane >> 4) * 8;
; #pragma unroll 4
;         for (int k = 0; k < D / 32; ++k) { const bf16x8 av = *(const bf16x8*)(a + 32 * k);
; #pragma unroll
;             for (int n = 0; n < NT; ++n) acc[n] = mfma16(av, *(const bf16x8*)(b + (size_t)n * 16 * D + 32 * k), acc[n]); }
; #pragma unroll
;         for (int n = 0; n < NT; ++n)
; #pragma unroll
;             for (int j = 0; j < 4; ++j) { const int row = rt * 16 + (lane >> 4) * 4 + j, col = n * 16 + (lane & 15); G[(size_t)row * (16 * NT) + col] = acc[n][j] * pg8::ep_rstd(rowss, row) + (bias ? bias[col] : 0.f); }
.LBB0_998:
	v_lshl_add_u64 v[20:21], v[18:19], 0, s[6:7]
	v_add_co_u32_e32 v28, vcc, 0xb000000, v20
	v_lshl_add_u64 v[24:25], v[12:13], 0, s[6:7]
	s_nop 0
	v_addc_co_u32_e32 v29, vcc, 0, v21, vcc
	v_add_co_u32_e32 v30, vcc, 0x600000, v24
	s_add_u32 s6, s6, 0x100
	s_nop 0
	v_addc_co_u32_e32 v31, vcc, 0, v25, vcc
	s_addc_u32 s7, s7, 0
	s_cmpk_eq_i32 s6, 0x1000
	global_load_dwordx4 v[80:83], v[28:29], off
	global_load_dwordx4 v[96:99], v[30:31], off
	global_load_dwordx4 v[84:87], v[28:29], off offset:64
	global_load_dwordx4 v[100:103], v[30:31], off offset:64
	global_load_dwordx4 v[88:91], v[28:29], off offset:128
	global_load_dwordx4 v[104:107], v[30:31], off offset:128
	global_load_dwordx4 v[92:95], v[28:29], off offset:192
	global_load_dwordx4 v[108:111], v[30:31], off offset:192
	s_waitcnt vmcnt(6) lgkmcnt(0)
	v_mfma_f32_16x16x32_bf16 v[6:9], v[80:83], v[96:99], v[6:9]
	s_waitcnt vmcnt(4)
	v_mfma_f32_16x16x32_bf16 v[6:9], v[84:87], v[100:103], v[6:9]
	s_waitcnt vmcnt(2)
	v_mfma_f32_16x16x32_bf16 v[6:9], v[88:91], v[104:107], v[6:9]
	s_waitcnt vmcnt(0)
	v_mfma_f32_16x16x32_bf16 v[6:9], v[92:95], v[108:111], v[6:9]
	s_cbranch_scc0 .LBB0_998
	v_lshl_or_b32 v18, s8, 4, v5
	v_ashrrev_i32_e32 v19, 31, v18
	v_lshl_add_u64 v[20:21], v[18:19], 3, s[0:1]
	global_load_dwordx2 v[20:21], v[20:21], off
	v_readlane_b32 s6, v255, 13
	v_readlane_b32 s7, v255, 14
	v_mov_b32_e32 v2, 0
	s_and_b64 vcc, exec, s[6:7]
	v_mov_b32_e32 v17, 0
	s_cbranch_vccz .LBB0_1001
	global_load_dword v17, v[10:11], off

; DI void rms_rows_f32(const Ctx& C, float* x, const float* g) {
;     for (int m = C.gw; m < T; m += C.ngw) {
;         f32x4* xr = (f32x4*)(x + (size_t)m * D) + C.lane; f32x4 v[8]; float s = 0.f;
; #pragma unroll
;         for (int j = 0; j < 8; ++j) { v[j] = xr[64 * j]; s += (v[j].x * v[j].x + v[j].y * v[j].y) + (v[j].z * v[j].z + v[j].w * v[j].w); }
;         const float rstd = 1.0f / sqrtf(wave_sum(s) * (1.0f / D) + EPS);
;         const f32x4* gr = (const f32x4*)g + C.lane;
; #pragma unroll
;         for (int j = 0; j < 8; ++j) { const f32x4 gv = gr[64 * j]; xr[64 * j] = v[j] * rstd * gv; }
;     }
.LBB0_1722:
	global_load_dwordx4 v[34:37], v[22:23], off
	global_load_dwordx4 v[4:7], v[22:23], off offset:1024
	global_load_dwordx4 v[38:41], v[22:23], off offset:2048
	global_load_dwordx4 v[42:45], v[22:23], off offset:3072
	v_add_co_u32_e32 v24, vcc, s7, v22
	s_add_i32 s6, s6, s24
	s_nop 0
	v_addc_co_u32_e32 v25, vcc, 0, v23, vcc
	global_load_dwordx4 v[8:11], v[24:25], off
	global_load_dwordx4 v[46:49], v[24:25], off offset:1024
	global_load_dwordx4 v[50:53], v[24:25], off offset:2048
	global_load_dwordx4 v[0:3], v[24:25], off offset:3072
	global_load_dwordx4 v[54:57], v[12:13], off
	s_cmpk_lt_i32 s6, 0x4000
	s_waitcnt vmcnt(0) lgkmcnt(0)
	v_mov_b32_e32 v60, v35
	v_mov_b32_e32 v61, v5
	v_mov_b32_e32 v64, v37
	v_mov_b32_e32 v65, v7
	v_mov_b32_e32 v58, v34
	v_mov_b32_e32 v59, v4
	v_mov_b32_e32 v62, v36
	v_mov_b32_e32 v63, v6
	v_pk_mul_f32 v[66:67], v[40:41], v[40:41]
	v_pk_mul_f32 v[68:69], v[38:39], v[38:39]
	v_pk_mul_f32 v[60:61], v[60:61], v[60:61]
	v_pk_mul_f32 v[64:65], v[64:65], v[64:65]
	v_pk_mov_b32 v[74:75], v[68:69], v[66:67] op_sel:[1,0]
	v_mov_b32_e32 v69, v67
	v_pk_fma_f32 v[58:59], v[58:59], v[58:59], v[60:61]
	v_pk_fma_f32 v[60:61], v[62:63], v[62:63], v[64:65]
	v_mul_f32_e32 v70, v43, v43
	v_mul_f32_e32 v72, v45, v45
	v_pk_add_f32 v[62:63], v[74:75], v[68:69]
	v_pk_add_f32 v[58:59], v[58:59], v[60:61]
	v_mul_f32_e32 v79, v8, v8
	v_mul_f32_e32 v81, v9, v9
	v_mul_f32_e32 v82, v10, v10
	v_mul_f32_e32 v83, v11, v11
	v_pk_fma_f32 v[66:67], v[42:43], v[42:43], v[70:71] op_sel_hi:[1,1,0]
	v_pk_fma_f32 v[70:71], v[44:45], v[44:45], v[72:73] op_sel_hi:[1,1,0]
	v_pk_add_f32 v[60:61], v[62:63], v[62:63] op_sel:[0,1] op_sel_hi:[1,0]
	v_pk_add_f32 v[58:59], v[58:59], v[58:59] op_sel:[0,1] op_sel_hi:[1,0]
	v_pk_mul_f32 v[72:73], v[48:49], v[48:49]
	v_pk_mul_f32 v[76:77], v[46:47], v[46:47]
	v_mov_b32_e32 v67, v82
	v_mov_b32_e32 v71, v83
	v_mov_b32_e32 v61, v81
	v_mov_b32_e32 v59, v79
	v_pk_mov_b32 v[64:65], v[76:77], v[72:73] op_sel:[1,0]
	v_mov_b32_e32 v77, v73
	v_pk_add_f32 v[62:63], v[66:67], v[70:71]
	v_pk_add_f32 v[58:59], v[58:59], v[60:61]
	v_mul_f32_e32 v78, v51, v51
	v_mul_f32_e32 v80, v53, v53
	v_pk_add_f32 v[64:65], v[64:65], v[76:77]
	v_pk_add_f32 v[58:59], v[58:59], v[62:63]
	v_mul_f32_e32 v84, v0, v0
	v_mul_f32_e32 v85, v1, v1
	v_mul_f32_e32 v86, v2, v2
	v_mul_f32_e32 v87, v3, v3
	v_pk_fma_f32 v[68:69], v[50:51], v[50:51], v[78:79] op_sel_hi:[1,1,0]
	v_pk_fma_f32 v[72:73], v[52:53], v[52:53], v[80:81] op_sel_hi:[1,1,0]
	v_pk_add_f32 v[64:65], v[64:65], v[64:65] op_sel:[0,1] op_sel_hi:[1,0]
	v_pk_add_f32 v[58:59], v[58:59], v[58:59] op_sel:[0,1] op_sel_hi:[1,0]
	v_mov_b32_e32 v69, v86
	v_mov_b32_e32 v73, v87
	v_mov_b32_e32 v65, v85
	v_mov_b32_e32 v59, v84
	v_pk_add_f32 v[66:67], v[68:69], v[72:73]
	v_pk_add_f32 v[58:59], v[58:59], v[64:65]
	s_nop 0
	v_pk_add_f32 v[58:59], v[58:59], v[66:67]
	s_nop 0
	v_add_f32_e32 v58, v58, v59
	ds_bpermute_b32 v59, v26, v58
	s_waitcnt lgkmcnt(0)
	v_add_f32_e32 v58, v58, v59
	ds_bpermute_b32 v59, v27, v58
	s_waitcnt lgkmcnt(0)
	v_add_f32_e32 v58, v58, v59
	ds_bpermute_b32 v59, v28, v58
	s_waitcnt lgkmcnt(0)
	v_add_f32_e32 v58, v58, v59
	ds_bpermute_b32 v59, v29, v58
	s_waitcnt lgkmcnt(0)
	v_add_f32_e32 v58, v58, v59
	ds_bpermute_b32 v59, v30, v58
	s_waitcnt lgkmcnt(0)
	v_add_f32_e32 v58, v58, v59
	ds_bpermute_b32 v59, v31, v58
	s_waitcnt lgkmcnt(0)
	v_add_f32_e32 v58, v58, v59
	v_fmamk_f32 v58, v58, 0x3a000000, v32
	v_mul_f32_e32 v59, 0x4f800000, v58
	v_cmp_gt_f32_e32 vcc, s8, v58
	s_nop 1
	v_cndmask_b32_e32 v58, v58, v59, vcc
	v_sqrt_f32_e32 v59, v58
	s_nop 0
	v_add_u32_e32 v60, -1, v59
	v_add_u32_e32 v61, 1, v59
	v_fma_f32 v62, -v60, v59, v58
	v_fma_f32 v63, -v61, v59, v58
	v_cmp_ge_f32_e64 s[0:1], 0, v62
	s_nop 1
	v_cndmask_b32_e64 v59, v59, v60, s[0:1]
	v_cmp_lt_f32_e64 s[0:1], 0, v63
	s_nop 1
	v_cndmask_b32_e64 v59, v59, v61, s[0:1]
	v_mul_f32_e32 v60, 0x37800000, v59
	v_cndmask_b32_e32 v59, v59, v60, vcc
	v_cmp_class_f32_e32 vcc, v58, v33
	s_nop 1
	v_cndmask_b32_e32 v58, v59, v58, vcc
	v_div_scale_f32 v59, s[0:1], v58, v58, 1.0
	v_rcp_f32_e32 v61, v59
	v_div_scale_f32 v60, vcc, 1.0, v58, 1.0
	v_fma_f32 v62, -v59, v61, 1.0
	v_fmac_f32_e32 v61, v62, v61
	v_mul_f32_e32 v62, v60, v61
	v_fma_f32 v63, -v59, v62, v60
	v_fmac_f32_e32 v62, v63, v61
	v_fma_f32 v59, -v59, v62, v60
	v_div_fmas_f32 v59, v59, v61, v62
	v_div_fixup_f32 v58, v59, v58, 1.0
	v_pk_mul_f32 v[34:35], v[34:35], v[58:59] op_sel_hi:[1,0]
	v_pk_mul_f32 v[36:37], v[36:37], v[58:59] op_sel_hi:[1,0]
	v_pk_mul_f32 v[34:35], v[54:55], v[34:35]
	v_pk_mul_f32 v[36:37], v[56:57], v[36:37]
	global_load_dwordx4 v[100:103], v[12:13], off offset:1024
	global_load_dwordx4 v[104:107], v[12:13], off offset:2048
	global_load_dwordx4 v[108:111], v[12:13], off offset:3072
	global_load_dwordx4 v[112:115], v[14:15], off
	global_load_dwordx4 v[116:119], v[16:17], off
	global_load_dwordx4 v[120:123], v[18:19], off
	global_load_dwordx4 v[124:127], v[20:21], off
	global_store_dwordx4 v[22:23], v[34:37], off
	v_pk_mul_f32 v[6:7], v[6:7], v[58:59] op_sel_hi:[1,0]
	v_pk_mul_f32 v[4:5], v[4:5], v[58:59] op_sel_hi:[1,0]
	v_pk_mul_f32 v[10:11], v[10:11], v[58:59] op_sel_hi:[1,0]
	v_pk_mul_f32 v[8:9], v[8:9], v[58:59] op_sel_hi:[1,0]
	v_pk_mul_f32 v[2:3], v[2:3], v[58:59] op_sel_hi:[1,0]
	v_pk_mul_f32 v[0:1], v[0:1], v[58:59] op_sel_hi:[1,0]
	s_waitcnt vmcnt(7)
	v_pk_mul_f32 v[4:5], v[100:101], v[4:5]
	v_pk_mul_f32 v[6:7], v[102:103], v[6:7]
	global_store_dwordx4 v[22:23], v[4:7], off offset:1024
	v_pk_mul_f32 v[34:35], v[40:41], v[58:59] op_sel_hi:[1,0]
	v_pk_mul_f32 v[36:37], v[38:39], v[58:59] op_sel_hi:[1,0]
	s_waitcnt vmcnt(7)
	v_pk_mul_f32 v[6:7], v[106:107], v[34:35]
	v_pk_mul_f32 v[4:5], v[104:105], v[36:37]
	global_store_dwordx4 v[22:23], v[4:7], off offset:2048
	v_pk_mul_f32 v[34:35], v[44:45], v[58:59] op_sel_hi:[1,0]
	v_pk_mul_f32 v[36:37], v[42:43], v[58:59] op_sel_hi:[1,0]
	s_waitcnt vmcnt(7)
	v_pk_mul_f32 v[6:7], v[110:111], v[34:35]
	v_pk_mul_f32 v[4:5], v[108:109], v[36:37]
	global_store_dwordx4 v[22:23], v[4:7], off offset:3072
	v_lshl_add_u64 v[22:23], v[22:23], 0, s[4:5]
	s_waitcnt vmcnt(7)
	v_pk_mul_f32 v[4:5], v[112:113], v[8:9]
	v_pk_mul_f32 v[6:7], v[114:115], v[10:11]
	global_store_dwordx4 v[24:25], v[4:7], off
	v_pk_mul_f32 v[8:9], v[48:49], v[58:59] op_sel_hi:[1,0]
	v_pk_mul_f32 v[10:11], v[46:47], v[58:59] op_sel_hi:[1,0]
	s_waitcnt vmcnt(7)
	v_pk_mul_f32 v[6:7], v[118:119], v[8:9]
	v_pk_mul_f32 v[4:5], v[116:117], v[10:11]
	global_store_dwordx4 v[24:25], v[4:7], off offset:1024
	v_pk_mul_f32 v[8:9], v[52:53], v[58:59] op_sel_hi:[1,0]
	v_pk_mul_f32 v[10:11], v[50:51], v[58:59] op_sel_hi:[1,0]
	s_waitcnt vmcnt(7)
	v_pk_mul_f32 v[6:7], v[8:9], v[122:123]
	v_pk_mul_f32 v[4:5], v[10:11], v[120:121]
	global_store_dwordx4 v[24:25], v[4:7], off offset:2048
	s_waitcnt vmcnt(7)
	v_pk_mul_f32 v[0:1], v[0:1], v[124:125]
	v_pk_mul_f32 v[2:3], v[2:3], v[126:127]
	global_store_dwordx4 v[24:25], v[0:3], off offset:3072
	s_cbranch_scc1 .LBB0_1722
